# GLA chunk loop: prefetch the 9 PART reads right after the first barrier into dead fragment registers; batch the epilogue's first two LDS reads
# baseline (speedup 1.0000x reference)
; #define LAS __attribute__((address_space(3)))
; #define LDS_BARRIER() asm volatile("s_waitcnt lgkmcnt(0)\n\ts_barrier" ::: "memory")
; #define GLA_GLOAD(CC) do { const size_t row_ = (size_t)b * SEQ + (CC) * 64 + tt * 16 + fr; \
;         _Pragma("unroll") for (int i = 0; i < 4; ++i) gpre[i] = *(const u32x2*)(P + row_ * 4096 + 3072 + h * 128 + (eh * 4 + i) * 16 + fq * 4); } while (0)
; __device__ __forceinline__ void gla_phase(LAS unsigned char* lds, const bf16_t* P, const float* hn, bf16_t* O, int G, int wg) {
;     ...
;             { const int cn = (c < 31) ? c + 1 : 31;
;               const bf16_t* pp = pbase + (size_t)(cn * 64 + tq * 8) * 4096;
; #pragma unroll
;                 for (int i = 0; i < 8; ++i) { rq[i] = *(const unsigned*)(pp + (size_t)i * 4096); rl[i] = *(const unsigned*)(pp + (size_t)i * 4096 + 1024); rv[i] = *(const unsigned*)(pp + (size_t)i * 4096 + 2048); } }
;             *(LAS f32x2*)(lds + PART + (tq * 128 + 2 * dp) * 4) = (f32x2){run0, run1};
;             LDS_BARRIER();
;             if (c > 0) GLA_EPILOGUE(c - 1);
;             GLA_GLOAD(c);
;             float off0 = 0.f, off1 = 0.f, bm0 = 0.f, bm1 = 0.f;
; #pragma unroll
;             for (int s2 = 0; s2 < 4; ++s2) { const f32x2 p = *(const LAS f32x2*)(lds + PART + (s2 * 128 + 2 * dp) * 4); if (s2 < tq) { off0 += p.x; off1 += p.y; } bm0 += p.x; bm1 += p.y; }
; #pragma unroll
;             for (int s2 = 4; s2 < 7; ++s2) { const f32x2 p = *(const LAS f32x2*)(lds + PART + (s2 * 128 + 2 * dp) * 4); if (s2 < tq) { off0 += p.x; off1 += p.y; } }
;             f32x4 cm4;
;             { f32x4 bm4 = (f32x4){0.f, 0.f, 0.f, 0.f};
; #pragma unroll
;               for (int s2 = 0; s2 < 4; ++s2) bm4 += *(const LAS f32x4*)(lds + PART + (s2 * 128 + wid * 16 + fq * 4) * 4);
.LBB0_1402:
	s_add_i32 s94, s95, 64
	s_cmpk_eq_i32 s95, 0x7c0
	s_cselect_b32 s16, s95, s94
	v_add_u32_e32 v16, s16, v82
	v_ashrrev_i32_e32 v17, 31, v16
	v_lshlrev_b64 v[16:17], 13, v[16:17]
	v_lshl_add_u64 v[16:17], v[102:103], 0, v[16:17]
	v_add_co_u32_e32 v18, vcc, s23, v16
	s_waitcnt vmcnt(20)
	v_lshlrev_b32_e32 v40, 16, v93
	v_addc_co_u32_e32 v19, vcc, 0, v17, vcc
	v_add_co_u32_e32 v20, vcc, s31, v16
	v_and_b32_e32 v41, 0xffff0000, v93
	s_nop 0
	v_addc_co_u32_e32 v21, vcc, 0, v17, vcc
	v_add_co_u32_e32 v22, vcc, s33, v16
	s_waitcnt vmcnt(17)
	v_lshlrev_b32_e32 v42, 16, v97
	v_addc_co_u32_e32 v23, vcc, 0, v17, vcc
	v_add_co_u32_e32 v24, vcc, s19, v16
	v_and_b32_e32 v43, 0xffff0000, v97
	s_nop 0
	v_addc_co_u32_e32 v25, vcc, 0, v17, vcc
	v_add_co_u32_e32 v26, vcc, s92, v16
	s_waitcnt vmcnt(14)
	v_lshlrev_b32_e32 v44, 16, v185
	v_addc_co_u32_e32 v27, vcc, 0, v17, vcc
	v_and_b32_e32 v45, 0xffff0000, v185
	global_load_dword v191, v[22:23], off
	global_load_dword v93, v[22:23], off offset:2048
	global_load_dword v194, v[24:25], off offset:-4096
	global_load_dword v192, v[24:25], off
	global_load_dword v97, v[24:25], off offset:2048
	global_load_dword v195, v[26:27], off offset:-4096
	global_load_dword v193, v[26:27], off
	global_load_dword v185, v[26:27], off offset:2048
	v_add_co_u32_e32 v24, vcc, 0xb000, v16
	s_waitcnt vmcnt(14)
	v_lshlrev_b32_e32 v34, 16, v189
	v_addc_co_u32_e32 v25, vcc, 0, v17, vcc
	v_add_co_u32_e32 v26, vcc, s12, v16
	v_and_b32_e32 v35, 0xffff0000, v189
	s_nop 0
	v_addc_co_u32_e32 v27, vcc, 0, v17, vcc
	v_add_co_u32_e32 v28, vcc, 0xd000, v16
	v_lshlrev_b32_e32 v46, 16, v187
	s_nop 0
	v_addc_co_u32_e32 v29, vcc, 0, v17, vcc
	v_add_co_u32_e32 v30, vcc, 0xe000, v16
	v_and_b32_e32 v47, 0xffff0000, v187
	s_nop 0
	v_addc_co_u32_e32 v31, vcc, 0, v17, vcc
	v_lshlrev_b32_e32 v48, 16, v188
	v_and_b32_e32 v49, 0xffff0000, v188
	global_load_dword v197, v[16:17], off
	global_load_dword v189, v[16:17], off offset:2048
	global_load_dword v199, v[24:25], off
	global_load_dword v196, v[26:27], off
	global_load_dword v187, v[26:27], off offset:2048
	global_load_dword v201, v[28:29], off
	global_load_dword v198, v[30:31], off
	global_load_dword v188, v[30:31], off offset:2048
	v_add_co_u32_e32 v16, vcc, 0xf000, v16
	s_waitcnt vmcnt(19)
	v_lshlrev_b32_e32 v36, 16, v190
	v_and_b32_e32 v37, 0xffff0000, v190
	v_lshlrev_b32_e32 v38, 16, v186
	v_and_b32_e32 v39, 0xffff0000, v186
	v_addc_co_u32_e32 v17, vcc, 0, v17, vcc
	global_load_dword v203, v[18:19], off offset:-4096
	global_load_dword v200, v[18:19], off
	global_load_dword v190, v[18:19], off offset:2048
	global_load_dword v204, v[20:21], off offset:-4096
	global_load_dword v202, v[20:21], off
	global_load_dword v186, v[20:21], off offset:2048
	global_load_dword v206, v[22:23], off offset:-4096
	global_load_dword v205, v[16:17], off
	v_pk_fma_f32 v[30:31], v[34:35], s[18:19], 0 op_sel_hi:[1,0,0]
	s_cmp_eq_u32 s95, 0
	v_pk_fma_f32 v[28:29], v[36:37], s[18:19], v[30:31] op_sel_hi:[1,0,1]
	s_mov_b32 s16, 0
	v_pk_fma_f32 v[26:27], v[38:39], s[18:19], v[28:29] op_sel_hi:[1,0,1]
	s_nop 0
	v_pk_fma_f32 v[24:25], v[40:41], s[18:19], v[26:27] op_sel_hi:[1,0,1]
	s_nop 0
	v_pk_fma_f32 v[22:23], v[42:43], s[18:19], v[24:25] op_sel_hi:[1,0,1]
	s_nop 0
	v_pk_fma_f32 v[20:21], v[44:45], s[18:19], v[22:23] op_sel_hi:[1,0,1]
	s_nop 0
	v_pk_fma_f32 v[18:19], v[46:47], s[18:19], v[20:21] op_sel_hi:[1,0,1]
	s_nop 0
	v_pk_fma_f32 v[16:17], v[48:49], s[18:19], v[18:19] op_sel_hi:[1,0,1]
	s_waitcnt lgkmcnt(0)
	s_barrier
	ds_write_b64 v161, v[16:17]
	s_waitcnt lgkmcnt(0)
	s_barrier
	v_add_u32_e32 v248, 0x1a000, v83
	ds_read2st64_b64 v[218:221], v248 offset1:1
	ds_read2st64_b64 v[222:225], v248 offset0:2 offset1:3
	ds_read_b64 v[226:227], v248 offset:2048
	ds_read_b64 v[228:229], v248 offset:2560
	ds_read_b64 v[230:231], v248 offset:3072
	ds_read_b128 v[232:235], v184
	ds_read_b128 v[236:239], v184 offset:512
	ds_read_b128 v[240:243], v184 offset:1024
	ds_read_b128 v[244:247], v184 offset:1536
	s_cbranch_scc1 .LBB0_1404
; #define LAS __attribute__((address_space(3)))
; __device__ __forceinline__ void gla_phase(LAS unsigned char* lds, const bf16_t* P, const float* hn, bf16_t* O, int G, int wg) {
;     ...
;             float off0 = 0.f, off1 = 0.f, bm0 = 0.f, bm1 = 0.f;
; #pragma unroll
;             for (int s2 = 0; s2 < 4; ++s2) { const f32x2 p = *(const LAS f32x2*)(lds + PART + (s2 * 128 + 2 * dp) * 4); if (s2 < tq) { off0 += p.x; off1 += p.y; } bm0 += p.x; bm1 += p.y; }
; #pragma unroll
;             for (int s2 = 4; s2 < 7; ++s2) { const f32x2 p = *(const LAS f32x2*)(lds + PART + (s2 * 128 + 2 * dp) * 4); if (s2 < tq) { off0 += p.x; off1 += p.y; } }
;             f32x4 cm4;
	ds_read2st64_b32 v[176:177], v146 offset1:1
	v_add_u32_e32 v56, 0x1b200, v147
	ds_read_b128 v[50:53], v56
	s_sub_i32 s16, s95, 64
	s_waitcnt lgkmcnt(1)
	v_add_f32_e32 v32, v176, v177
	v_fmamk_f32 v32, v32, 0x3c000000, v211
	v_rsq_f32_e32 v32, v32
	s_nop 0
	v_pk_mul_f32 v[12:13], v[12:13], v[32:33] op_sel_hi:[1,0]
	v_pk_mul_f32 v[8:9], v[8:9], v[32:33] op_sel_hi:[1,0]
	s_waitcnt lgkmcnt(0)
	v_pk_mul_f32 v[12:13], v[50:51], v[12:13]
	v_lshlrev_b32_e32 v50, 16, v142
	v_and_b32_e32 v51, 0xffff0000, v142
	v_pk_mul_f32 v[12:13], v[12:13], v[50:51]
	v_pk_mul_f32 v[4:5], v[4:5], v[32:33] op_sel_hi:[1,0]
	v_cvt_pk_bf16_f32 v50, v12, v13
	v_pk_mul_f32 v[12:13], v[14:15], v[32:33] op_sel_hi:[1,0]
	v_lshlrev_b32_e32 v14, 16, v143
	v_pk_mul_f32 v[12:13], v[52:53], v[12:13]
	v_and_b32_e32 v15, 0xffff0000, v143
	v_pk_mul_f32 v[12:13], v[12:13], v[14:15]
	v_pk_mul_f32 v[0:1], v[0:1], v[32:33] op_sel_hi:[1,0]
	v_cvt_pk_bf16_f32 v51, v12, v13
	ds_read_b128 v[12:15], v56 offset:64
	s_waitcnt lgkmcnt(0)
	v_pk_mul_f32 v[8:9], v[12:13], v[8:9]
	s_waitcnt vmcnt(26)
	v_lshlrev_b32_e32 v12, 16, v140
	v_and_b32_e32 v13, 0xffff0000, v140
	v_pk_mul_f32 v[8:9], v[8:9], v[12:13]
	s_nop 0
	v_cvt_pk_bf16_f32 v12, v8, v9
	v_pk_mul_f32 v[8:9], v[10:11], v[32:33] op_sel_hi:[1,0]
	v_lshlrev_b32_e32 v10, 16, v141
	v_pk_mul_f32 v[8:9], v[14:15], v[8:9]
	v_and_b32_e32 v11, 0xffff0000, v141
	v_pk_mul_f32 v[8:9], v[8:9], v[10:11]
	s_nop 0
	v_cvt_pk_bf16_f32 v13, v8, v9
	ds_read_b128 v[8:11], v56 offset:128
	s_waitcnt lgkmcnt(0)
	v_pk_mul_f32 v[4:5], v[8:9], v[4:5]
	s_waitcnt vmcnt(25)
	v_lshlrev_b32_e32 v8, 16, v114
	v_and_b32_e32 v9, 0xffff0000, v114
	v_pk_mul_f32 v[4:5], v[4:5], v[8:9]
	s_nop 0
	v_cvt_pk_bf16_f32 v8, v4, v5
	v_pk_mul_f32 v[4:5], v[6:7], v[32:33] op_sel_hi:[1,0]
	v_lshlrev_b32_e32 v6, 16, v115
	v_pk_mul_f32 v[4:5], v[10:11], v[4:5]
	v_and_b32_e32 v7, 0xffff0000, v115
	v_pk_mul_f32 v[4:5], v[4:5], v[6:7]
	s_nop 0
	v_cvt_pk_bf16_f32 v9, v4, v5
	ds_read_b128 v[4:7], v56 offset:192
	s_waitcnt lgkmcnt(0)
	v_pk_mul_f32 v[0:1], v[0:1], v[4:5]
	s_waitcnt vmcnt(24)
	v_lshlrev_b32_e32 v4, 16, v100
	v_and_b32_e32 v5, 0xffff0000, v100
	v_pk_mul_f32 v[0:1], v[0:1], v[4:5]
	s_nop 0
	v_cvt_pk_bf16_f32 v10, v0, v1
	v_pk_mul_f32 v[0:1], v[2:3], v[32:33] op_sel_hi:[1,0]
	v_lshlrev_b32_e32 v2, 16, v101
	v_pk_mul_f32 v[0:1], v[0:1], v[6:7]
	v_and_b32_e32 v3, 0xffff0000, v101
	v_pk_mul_f32 v[0:1], v[0:1], v[2:3]
	v_and_b32_e32 v3, 64, v213
	v_xor_b32_e32 v2, 16, v213
	v_add_u32_e32 v3, 64, v3
	v_cmp_lt_i32_e32 vcc, v2, v3
	v_cvt_pk_bf16_f32 v6, v0, v1
	v_lshl_add_u64 v[0:1], v[98:99], 0, s[16:17]
	v_cndmask_b32_e32 v2, v213, v2, vcc
	v_lshlrev_b32_e32 v7, 2, v2
	v_lshlrev_b64 v[4:5], 11, v[0:1]
	v_cndmask_b32_e64 v0, v50, v12, s[42:43]
	v_cndmask_b32_e64 v1, v51, v13, s[42:43]
	ds_bpermute_b32 v0, v7, v0
	ds_bpermute_b32 v1, v7, v1
	v_lshl_add_u64 v[4:5], v[104:105], 0, v[4:5]
	s_mov_b32 s16, s95
	s_waitcnt lgkmcnt(1)
	v_cndmask_b32_e64 v2, v12, v0, s[42:43]
	s_waitcnt lgkmcnt(0)
	v_cndmask_b32_e64 v3, v13, v1, s[42:43]
	v_cndmask_b32_e64 v1, v1, v51, s[42:43]
	v_cndmask_b32_e64 v0, v0, v50, s[42:43]
	global_store_dwordx4 v[4:5], v[0:3], off
	s_nop 1
	v_cndmask_b32_e64 v0, v8, v10, s[42:43]
	v_cndmask_b32_e64 v1, v9, v6, s[42:43]
	ds_bpermute_b32 v0, v7, v0
	ds_bpermute_b32 v1, v7, v1
	s_waitcnt lgkmcnt(1)
	v_cndmask_b32_e64 v2, v10, v0, s[42:43]
	s_waitcnt lgkmcnt(0)
	v_cndmask_b32_e64 v3, v6, v1, s[42:43]
	v_cndmask_b32_e64 v1, v1, v9, s[42:43]
	v_cndmask_b32_e64 v0, v0, v8, s[42:43]
	global_store_dwordx4 v[4:5], v[0:3], off offset:64
.LBB0_1404:
	v_or_b32_e32 v174, s16, v86
	s_nop 0
	v_lshl_add_u64 v[0:1], s[0:1], 0, v[174:175]
	v_lshlrev_b64 v[0:1], 13, v[0:1]
	v_lshl_add_u64 v[0:1], s[14:15], 0, v[0:1]
	s_lshl_b32 s16, s93, 1
	v_lshl_add_u64 v[0:1], v[0:1], 0, s[16:17]
	v_mov_b32_e32 v95, v175
	v_lshl_add_u64 v[0:1], v[0:1], 0, v[94:95]
	v_lshl_add_u64 v[0:1], v[88:89], 1, v[0:1]
	s_mov_b64 vcc, 0x1800
	v_lshl_add_u64 v[2:3], v[0:1], 0, vcc
	v_add_co_u32_e32 v0, vcc, 0x1000, v0
	s_nop 1
	v_addc_co_u32_e32 v1, vcc, 0, v1, vcc
	global_load_dwordx2 v[142:143], v[0:1], off offset:2048
	global_load_dwordx2 v[140:141], v[2:3], off offset:32
	global_load_dwordx2 v[114:115], v[2:3], off offset:64
	global_load_dwordx2 v[100:101], v[2:3], off offset:96
	s_waitcnt lgkmcnt(0)
	v_mov_b32_e32 v12, v218
	v_mov_b32_e32 v13, v219
	v_mov_b32_e32 v14, v220
	v_mov_b32_e32 v15, v221
	v_mov_b32_e32 v8, v222
	v_mov_b32_e32 v9, v223
	v_mov_b32_e32 v10, v224
	v_mov_b32_e32 v11, v225
	v_add_f32_e32 v0, 0, v12
	v_add_f32_e32 v79, 0, v13
	v_cndmask_b32_e64 v1, 0, v79, s[46:47]
	v_cndmask_b32_e64 v2, 0, v0, s[46:47]
	v_add_f32_e32 v3, v14, v2
	v_add_f32_e32 v4, v15, v1
	v_cndmask_b32_e64 v1, v1, v4, s[48:49]
	v_cndmask_b32_e64 v2, v2, v3, s[48:49]
	s_waitcnt lgkmcnt(0)
	v_add_f32_e32 v3, v8, v2
	v_add_f32_e32 v4, v9, v1
	v_cndmask_b32_e64 v1, v1, v4, s[50:51]
	v_cndmask_b32_e64 v4, v2, v3, s[50:51]
	v_add_f32_e32 v2, v10, v4
	v_add_f32_e32 v3, v11, v1
	v_cndmask_b32_e64 v32, v1, v3, s[52:53]
	v_cndmask_b32_e64 v77, v4, v2, s[52:53]
	v_add_u32_e32 v1, s8, v83
	s_and_saveexec_b64 vcc, s[54:55]
	s_cbranch_execz .LBB0_1414
	v_add_f32_e32 v77, v2, v226
	v_add_f32_e32 v32, v3, v227
	s_or_b64 exec, exec, vcc
	s_and_saveexec_b64 vcc, s[56:57]
	s_cbranch_execnz .LBB0_1415

; #define LAS __attribute__((address_space(3)))
; __device__ __forceinline__ void gla_phase(LAS unsigned char* lds, const bf16_t* P, const float* hn, bf16_t* O, int G, int wg) {
;     ...
;             float off0 = 0.f, off1 = 0.f, bm0 = 0.f, bm1 = 0.f;
; #pragma unroll
;             for (int s2 = 0; s2 < 4; ++s2) { const f32x2 p = *(const LAS f32x2*)(lds + PART + (s2 * 128 + 2 * dp) * 4); if (s2 < tq) { off0 += p.x; off1 += p.y; } bm0 += p.x; bm1 += p.y; }
; #pragma unroll
;             for (int s2 = 4; s2 < 7; ++s2) { const f32x2 p = *(const LAS f32x2*)(lds + PART + (s2 * 128 + 2 * dp) * 4); if (s2 < tq) { off0 += p.x; off1 += p.y; } }
;             f32x4 cm4;
;             { f32x4 bm4 = (f32x4){0.f, 0.f, 0.f, 0.f};
; #pragma unroll
;               for (int s2 = 0; s2 < 4; ++s2) bm4 += *(const LAS f32x4*)(lds + PART + (s2 * 128 + wid * 16 + fq * 4) * 4);
; #pragma unroll
;               for (int j = 0; j < 4; ++j) cm4[j] = __builtin_amdgcn_exp2f(bm4[j]); }
; #pragma unroll
;             for (int e = 0; e < 8; ++e) { const int et = ((e < 4) ? eh : (eh ^ 1)) * 4 + (e & 3);
;                 u32x2 w; w.x = pk2(sacc[e][0] * cm4[0], sacc[e][1] * cm4[1]); w.y = pk2(sacc[e][2] * cm4[2], sacc[e][3] * cm4[3]);
;                 *(LAS u32x2*)(lds + ST + (et * 16 + fr) * 256 + (((wid * 2 + (fq >> 1)) ^ fr) << 4) + (fq & 1) * 8) = w; }
;             unsigned kt0[4], kt1[4];
; #pragma unroll
;             for (int i = 0; i < 8; i += 2) {
;                 float k0v[2], k1v[2];
; #pragma unroll
;                 for (int z = 0; z < 2; ++z) {
;                     const int ii = i + z, t = tq * 8 + ii; const float x0 = b0[ii] + off0 - bm0, x1 = b1[ii] + off1 - bm1;
;                     const float kv0 = 1.f - __builtin_amdgcn_exp2f(l0[ii]), kv1 = 1.f - __builtin_amdgcn_exp2f(l1[ii]);
;                     const float e10 = __builtin_amdgcn_exp2f(fminf(x0, 80.f)), e20 = __builtin_amdgcn_exp2f(fminf(-x0, 80.f));
;                     const float e11 = __builtin_amdgcn_exp2f(fminf(x1, 80.f)), e21 = __builtin_amdgcn_exp2f(fminf(-x1, 80.f));
;                     k0v[z] = kv0 * e20; k1v[z] = kv1 * e21;
;                     const int wo = t * 256 + ((((dp >> 2) ^ (t & 15))) << 4) + (dp & 3) * 4;
;                     *(LAS unsigned*)(lds + QT + wo) = pk2(q0[ii] * e10, q1[ii] * e11);
;                     *(LAS unsigned*)(lds + KT + wo) = pk2(k0v[z], k1v[z]);
;                 }
.LBB0_1407:
	v_add_f32_e32 v77, v77, v230
	v_add_f32_e32 v32, v32, v231
.LBB0_1408:
	s_or_b64 exec, exec, vcc
	v_and_b32_e32 v1, 0xffff, v33
	v_and_b32_e32 v2, 0xffff, v65
	v_lshl_or_b32 v5, v64, 16, v1
	v_lshrrev_b32_e32 v1, 16, v33
	v_lshl_or_b32 v6, v66, 16, v2
	v_lshrrev_b32_e32 v2, 16, v65
	v_and_b32_e32 v3, 0xffff, v67
	v_and_or_b32 v1, v64, s37, v1
	v_and_or_b32 v2, v66, s37, v2
	s_waitcnt vmcnt(28)
	v_lshl_or_b32 v7, v69, 16, v3
	v_lshrrev_b32_e32 v3, 16, v67
	v_add_f32_e32 v0, v0, v14
	v_add_f32_e32 v0, v0, v8
	v_add_f32_e32 v78, v0, v10
	v_and_b32_e32 v0, 0xffff, v68
	v_lshl_or_b32 v4, v70, 16, v0
	v_lshrrev_b32_e32 v0, 16, v68
	v_and_or_b32 v3, v69, s37, v3
	v_add_f32_e32 v8, v79, v15
	s_waitcnt lgkmcnt(0)
	v_pk_add_f32 v[14:15], v[234:235], 0 op_sel_hi:[1,0]
	v_pk_add_f32 v[68:69], v[232:233], 0 op_sel_hi:[1,0]
	v_pk_mul_f32 v[62:63], v[34:35], s[18:19] op_sel_hi:[1,0]
	v_pk_mul_f32 v[34:35], v[48:49], s[18:19] op_sel_hi:[1,0]
	v_lshlrev_b32_e32 v48, 16, v71
	v_and_b32_e32 v49, 0xffff0000, v71
	s_waitcnt lgkmcnt(0)
	v_pk_add_f32 v[14:15], v[14:15], v[238:239]
	v_pk_add_f32 v[68:69], v[68:69], v[236:237]
	v_and_or_b32 v0, v70, s37, v0
	v_add_f32_e32 v9, v8, v9
	v_add_u32_e32 v8, v149, v148
	v_mov_b32_e32 v33, v11
	s_waitcnt lgkmcnt(0)
	v_pk_add_f32 v[14:15], v[14:15], v[242:243]
	v_pk_add_f32 v[68:69], v[68:69], v[240:241]
	v_lshlrev_b32_e32 v60, 16, v54
	v_and_b32_e32 v61, 0xffff0000, v54
	v_pk_mul_f32 v[58:59], v[36:37], s[18:19] op_sel_hi:[1,0]
	v_pk_mul_f32 v[56:57], v[38:39], s[18:19] op_sel_hi:[1,0]
	s_waitcnt lgkmcnt(0)
	v_pk_add_f32 v[14:15], v[14:15], v[246:247]
	v_pk_add_f32 v[64:65], v[68:69], v[244:245]
	v_exp_f32_e32 v14, v14
	v_exp_f32_e32 v64, v64
	v_exp_f32_e32 v65, v65
	v_exp_f32_e32 v15, v15
	v_lshlrev_b32_e32 v12, 16, v55
	v_and_b32_e32 v13, 0xffff0000, v55
	v_pk_mul_f32 v[66:67], v[106:107], v[64:65]
	v_pk_mul_f32 v[68:69], v[108:109], v[14:15]
	v_cvt_pk_bf16_f32 v66, v66, v67
	v_cvt_pk_bf16_f32 v67, v68, v69
	v_pk_mul_f32 v[68:69], v[110:111], v[64:65]
	v_pk_mul_f32 v[70:71], v[112:113], v[14:15]
	v_cvt_pk_bf16_f32 v68, v68, v69
	v_cvt_pk_bf16_f32 v69, v70, v71
	ds_write2st64_b64 v8, v[66:67], v[68:69] offset0:64 offset1:72
	v_pk_mul_f32 v[66:67], v[116:117], v[64:65]
	v_pk_mul_f32 v[68:69], v[118:119], v[14:15]
	v_cvt_pk_bf16_f32 v66, v66, v67
	v_cvt_pk_bf16_f32 v67, v68, v69
	v_pk_mul_f32 v[68:69], v[120:121], v[64:65]
	v_pk_mul_f32 v[70:71], v[122:123], v[14:15]
	v_cvt_pk_bf16_f32 v68, v68, v69
	v_cvt_pk_bf16_f32 v69, v70, v71
	ds_write2st64_b64 v8, v[66:67], v[68:69] offset0:80 offset1:88
	v_pk_mul_f32 v[66:67], v[124:125], v[64:65]
	v_pk_mul_f32 v[68:69], v[126:127], v[14:15]
	v_cvt_pk_bf16_f32 v66, v66, v67
	v_cvt_pk_bf16_f32 v67, v68, v69
	v_pk_mul_f32 v[68:69], v[128:129], v[64:65]
	v_pk_mul_f32 v[70:71], v[130:131], v[14:15]
	v_cvt_pk_bf16_f32 v68, v68, v69
	v_cvt_pk_bf16_f32 v69, v70, v71
	ds_write2st64_b64 v162, v[66:67], v[68:69] offset0:64 offset1:72
	v_pk_mul_f32 v[66:67], v[132:133], v[64:65]
	v_pk_mul_f32 v[68:69], v[134:135], v[14:15]
	v_pk_mul_f32 v[64:65], v[136:137], v[64:65]
	v_pk_mul_f32 v[14:15], v[138:139], v[14:15]
	v_add_f32_e32 v8, v30, v77
	v_cvt_pk_bf16_f32 v64, v64, v65
	v_cvt_pk_bf16_f32 v65, v14, v15
	v_sub_f32_e32 v14, v8, v78
	v_mov_b32_e32 v8, v31
	v_pk_add_f32 v[10:11], v[8:9], v[32:33]
	v_exp_f32_e32 v8, v62
	v_sub_f32_e32 v10, v10, v11
	v_min_f32_e64 v9, -v14, s91
	v_cvt_pk_bf16_f32 v66, v66, v67
	v_sub_f32_e32 v15, 1.0, v8
	v_exp_f32_e32 v8, v63
	v_cvt_pk_bf16_f32 v67, v68, v69
	ds_write2st64_b64 v162, v[66:67], v[64:65] offset0:80 offset1:88
	v_lshlrev_b32_e32 v54, 16, v76
	v_sub_f32_e32 v30, 1.0, v8
	v_min_f32_e32 v8, 0x42a00000, v14
	v_exp_f32_e32 v14, v9
	v_min_f32_e32 v9, 0x42a00000, v10
	v_min_f32_e64 v10, -v10, s91
	v_exp_f32_e32 v8, v8
	v_exp_f32_e32 v9, v9
	v_exp_f32_e32 v10, v10
	v_mul_f32_e32 v31, v15, v14
	v_and_b32_e32 v55, 0xffff0000, v76
	v_pk_mul_f32 v[8:9], v[8:9], v[60:61]
	v_mul_f32_e32 v10, v30, v10
	v_cvt_pk_bf16_f32 v8, v8, v9
	v_cvt_pk_bf16_f32 v9, v31, v10
	ds_write2st64_b32 v163, v8, v9 offset1:64
	v_add_f32_e32 v8, v28, v77
	v_sub_f32_e32 v15, v8, v78
	v_add_f32_e32 v8, v29, v32
	v_sub_f32_e32 v29, v8, v11
	v_min_f32_e32 v14, 0x42a00000, v15
	v_min_f32_e64 v15, -v15, s91
	v_exp_f32_e32 v8, v58
	v_exp_f32_e32 v9, v59
	v_exp_f32_e32 v28, v15
	v_min_f32_e32 v15, 0x42a00000, v29
	v_min_f32_e64 v29, -v29, s91
	v_exp_f32_e32 v14, v14
	v_exp_f32_e32 v15, v15
	v_exp_f32_e32 v29, v29
	v_pk_add_f32 v[8:9], v[8:9], 1.0 op_sel_hi:[1,0] neg_lo:[1,0] neg_hi:[1,0]
	v_pk_mul_f32 v[52:53], v[40:41], s[18:19] op_sel_hi:[1,0]
	v_pk_mul_f32 v[12:13], v[14:15], v[12:13]
	v_pk_mul_f32 v[8:9], v[8:9], v[28:29]
	v_exp_f32_e32 v14, v57
	v_cvt_pk_bf16_f32 v12, v12, v13
	v_cvt_pk_bf16_f32 v13, v8, v9
	ds_write2st64_b32 v164, v12, v13 offset1:64
	v_cvt_pk_bf16_f32 v12, v31, v8
	v_cvt_pk_bf16_f32 v8, v10, v9
	v_add_f32_e32 v9, v26, v77
	v_add_f32_e32 v10, v27, v32
	v_sub_f32_e32 v9, v9, v78
	v_sub_f32_e32 v10, v10, v11
	v_exp_f32_e32 v13, v56
	v_sub_f32_e32 v26, 1.0, v14
	v_min_f32_e32 v14, 0x42a00000, v9
	v_min_f32_e64 v9, -v9, s91
	v_min_f32_e32 v15, 0x42a00000, v10
	v_min_f32_e64 v10, -v10, s91
	v_exp_f32_e32 v14, v14
	v_exp_f32_e32 v9, v9
	v_exp_f32_e32 v15, v15
	v_exp_f32_e32 v10, v10
	v_sub_f32_e32 v13, 1.0, v13
	v_mul_f32_e32 v9, v13, v9
	v_pk_mul_f32 v[14:15], v[14:15], v[54:55]
	v_mul_f32_e32 v10, v26, v10
	v_cvt_pk_bf16_f32 v13, v14, v15
	v_cvt_pk_bf16_f32 v14, v9, v10
	ds_write2st64_b32 v165, v13, v14 offset1:64
; __device__ __forceinline__ void gla_phase(LAS unsigned char* lds, const bf16_t* P, const float* hn, bf16_t* O, int G, int wg) {
;     ...
;             unsigned kt0[4], kt1[4];
; #pragma unroll
;             for (int i = 0; i < 8; i += 2) {
;                 float k0v[2], k1v[2];
; #pragma unroll
;                 for (int z = 0; z < 2; ++z) {
;                     const int ii = i + z, t = tq * 8 + ii; const float x0 = b0[ii] + off0 - bm0, x1 = b1[ii] + off1 - bm1;
;                     const float kv0 = 1.f - __builtin_amdgcn_exp2f(l0[ii]), kv1 = 1.f - __builtin_amdgcn_exp2f(l1[ii]);
;                     const float e10 = __builtin_amdgcn_exp2f(fminf(x0, 80.f)), e20 = __builtin_amdgcn_exp2f(fminf(-x0, 80.f));
;                     const float e11 = __builtin_amdgcn_exp2f(fminf(x1, 80.f)), e21 = __builtin_amdgcn_exp2f(fminf(-x1, 80.f));
;                     k0v[z] = kv0 * e20; k1v[z] = kv1 * e21;
;                     const int wo = t * 256 + ((((dp >> 2) ^ (t & 15))) << 4) + (dp & 3) * 4;
;                     *(LAS unsigned*)(lds + QT + wo) = pk2(q0[ii] * e10, q1[ii] * e11);
;                     *(LAS unsigned*)(lds + KT + wo) = pk2(k0v[z], k1v[z]);
;                 }
;                 kt0[i >> 1] = pk2(k0v[0], k0v[1]); kt1[i >> 1] = pk2(k1v[0], k1v[1]);
;             }
;             { const int so = (2 * dp) * 128 + ((tq ^ (dp & 7)) << 4); constexpr int TS = 128;
;               LAS unsigned char* dk = lds + KTT + so; LAS unsigned char* dv = lds + VT + so;
;               *(LAS u32x4*)dk = (u32x4){kt0[0], kt0[1], kt0[2], kt0[3]}; *(LAS u32x4*)(dk + TS) = (u32x4){kt1[0], kt1[1], kt1[2], kt1[3]};
;               *(LAS u32x4*)dv = (u32x4){vt0[0], vt0[1], vt0[2], vt0[3]}; *(LAS u32x4*)(dv + TS) = (u32x4){vt1[0], vt1[1], vt1[2], vt1[3]}; }
;             LDS_BARRIER();
;             { const int st = wid & 3, tA = (wid >> 2) * 2;
;               bf16x8 kA[4], qA[2][4], qB[4], sB[4][4];
; #pragma unroll
;               for (int ks = 0; ks < 4; ++ks) { kA[ks] = FRAGK(KT, st, ks); qA[0][ks] = FRAGK(QT, tA, ks); qA[1][ks] = FRAGK(QT, tA + 1, ks); }
; #pragma unroll
;               for (int ks = 0; ks < 4; ++ks) qB[ks] = FRAGK(QT, tt, ks);
;               __builtin_amdgcn_sched_barrier(0);
;               f32x4 accA[2];
; #pragma unroll
;               for (int z = 0; z < 2; ++z) { accA[z] = (f32x4){0.f, 0.f, 0.f, 0.f};
;                 if (tA + z >= st) {
	v_add_f32_e32 v13, v24, v77
	v_sub_f32_e32 v13, v13, v78
	v_add_f32_e32 v14, v25, v32
	v_sub_f32_e32 v27, v14, v11
	v_min_f32_e32 v24, 0x42a00000, v13
	v_min_f32_e64 v13, -v13, s91
	v_exp_f32_e32 v26, v13
	v_min_f32_e32 v13, 0x42a00000, v27
	v_exp_f32_e32 v14, v52
	v_exp_f32_e32 v15, v53
	v_exp_f32_e32 v25, v13
	v_min_f32_e64 v13, -v27, s91
	v_exp_f32_e32 v24, v24
	v_exp_f32_e32 v27, v13
	v_pk_add_f32 v[14:15], v[14:15], 1.0 op_sel_hi:[1,0] neg_lo:[1,0] neg_hi:[1,0]
	v_pk_mul_f32 v[50:51], v[42:43], s[18:19] op_sel_hi:[1,0]
	v_pk_mul_f32 v[24:25], v[24:25], v[48:49]
	v_pk_mul_f32 v[14:15], v[14:15], v[26:27]
	v_cvt_pk_bf16_f32 v13, v24, v25
	v_cvt_pk_bf16_f32 v24, v14, v15
	ds_write2st64_b32 v166, v13, v24 offset1:64
	v_cvt_pk_bf16_f32 v13, v9, v14
	v_add_f32_e32 v14, v23, v32
	v_cvt_pk_bf16_f32 v9, v10, v15
	v_add_f32_e32 v10, v22, v77
	v_sub_f32_e32 v22, v14, v11
	v_exp_f32_e32 v14, v50
	v_sub_f32_e32 v10, v10, v78
	v_min_f32_e32 v15, 0x42a00000, v22
	v_min_f32_e64 v22, -v22, s91
	v_sub_f32_e32 v23, 1.0, v14
	v_exp_f32_e32 v14, v51
	v_exp_f32_e32 v15, v15
	v_exp_f32_e32 v22, v22
	v_pk_mul_f32 v[40:41], v[46:47], s[18:19] op_sel_hi:[1,0]
	v_sub_f32_e32 v24, 1.0, v14
	v_min_f32_e32 v14, 0x42a00000, v10
	v_min_f32_e64 v10, -v10, s91
	v_exp_f32_e32 v14, v14
	v_exp_f32_e32 v10, v10
	v_lshlrev_b32_e32 v46, 16, v72
	v_and_b32_e32 v47, 0xffff0000, v72
	v_mul_f32_e32 v24, v24, v22
	v_mul_f32_e32 v10, v23, v10
	v_pk_mul_f32 v[14:15], v[14:15], v[46:47]
	v_pk_mul_f32 v[44:45], v[44:45], s[18:19] op_sel_hi:[1,0]
	v_cvt_pk_bf16_f32 v14, v14, v15
	v_cvt_pk_bf16_f32 v15, v10, v24
	ds_write2st64_b32 v167, v14, v15 offset1:64
	v_add_f32_e32 v14, v20, v77
	v_sub_f32_e32 v22, v14, v78
	v_add_f32_e32 v14, v21, v32
	v_sub_f32_e32 v23, v14, v11
	v_min_f32_e64 v21, -v22, s91
	v_exp_f32_e32 v14, v44
	v_exp_f32_e32 v15, v45
	v_min_f32_e32 v20, 0x42a00000, v22
	v_exp_f32_e32 v22, v21
	v_min_f32_e32 v21, 0x42a00000, v23
	v_min_f32_e64 v23, -v23, s91
	v_exp_f32_e32 v20, v20
	v_exp_f32_e32 v21, v21
	v_exp_f32_e32 v23, v23
	v_lshlrev_b32_e32 v42, 16, v73
	v_and_b32_e32 v43, 0xffff0000, v73
	v_pk_add_f32 v[14:15], v[14:15], 1.0 op_sel_hi:[1,0] neg_lo:[1,0] neg_hi:[1,0]
	v_pk_mul_f32 v[20:21], v[20:21], v[42:43]
	v_pk_mul_f32 v[14:15], v[14:15], v[22:23]
	v_cvt_pk_bf16_f32 v20, v20, v21
	v_cvt_pk_bf16_f32 v21, v14, v15
	v_cvt_pk_bf16_f32 v14, v10, v14
	v_cvt_pk_bf16_f32 v10, v24, v15
	v_add_f32_e32 v15, v18, v77
	v_add_f32_e32 v18, v19, v32
	ds_write2st64_b32 v168, v20, v21 offset1:64
	v_sub_f32_e32 v20, v18, v11
	v_exp_f32_e32 v18, v40
	v_sub_f32_e32 v15, v15, v78
	v_min_f32_e32 v19, 0x42a00000, v20
	v_min_f32_e64 v20, -v20, s91
	v_sub_f32_e32 v21, 1.0, v18
	v_exp_f32_e32 v18, v41
	v_exp_f32_e32 v19, v19
	v_exp_f32_e32 v20, v20
	v_lshlrev_b32_e32 v38, 16, v74
	v_sub_f32_e32 v22, 1.0, v18
	v_min_f32_e32 v18, 0x42a00000, v15
	v_min_f32_e64 v15, -v15, s91
	v_exp_f32_e32 v18, v18
	v_exp_f32_e32 v15, v15
	v_and_b32_e32 v39, 0xffff0000, v74
	v_mul_f32_e32 v22, v22, v20
	v_pk_mul_f32 v[18:19], v[18:19], v[38:39]
	v_mul_f32_e32 v15, v21, v15
	v_cvt_pk_bf16_f32 v18, v18, v19
	v_cvt_pk_bf16_f32 v19, v15, v22
	v_add_f32_e32 v16, v16, v77
	ds_write2st64_b32 v169, v18, v19 offset1:64
	v_sub_f32_e32 v19, v16, v78
	v_add_f32_e32 v16, v17, v32
	v_sub_f32_e32 v11, v16, v11
	v_min_f32_e32 v18, 0x42a00000, v19
	v_min_f32_e64 v19, -v19, s91
	v_exp_f32_e32 v16, v34
	v_exp_f32_e32 v17, v35
	v_exp_f32_e32 v20, v19
	v_min_f32_e32 v19, 0x42a00000, v11
	v_min_f32_e64 v11, -v11, s91
	v_exp_f32_e32 v18, v18
	v_exp_f32_e32 v19, v19
	v_exp_f32_e32 v21, v11
	v_lshlrev_b32_e32 v36, 16, v75
	v_and_b32_e32 v37, 0xffff0000, v75
	v_pk_add_f32 v[16:17], v[16:17], 1.0 op_sel_hi:[1,0] neg_lo:[1,0] neg_hi:[1,0]
	v_pk_mul_f32 v[18:19], v[18:19], v[36:37]
	v_pk_mul_f32 v[16:17], v[16:17], v[20:21]
	v_cvt_pk_bf16_f32 v11, v18, v19
	v_cvt_pk_bf16_f32 v18, v16, v17
	v_cvt_pk_bf16_f32 v15, v15, v16
	v_add_u32_e32 v16, 0x10000, v171
	ds_write2st64_b32 v170, v11, v18 offset1:64
	v_cvt_pk_bf16_f32 v11, v22, v17
	ds_write_b128 v16, v[12:15]
	ds_write_b128 v16, v[8:11] offset:128
	v_add_u32_e32 v8, 0x14000, v171
	ds_write_b128 v8, v[4:7]
	ds_write_b128 v8, v[0:3] offset:128
	s_waitcnt lgkmcnt(0)
	s_barrier
	v_add_u32_e32 v0, v150, v144
	v_add_u32_e32 v1, v151, v144
	ds_read_b128 v[20:23], v0 offset:16384
	ds_read_b128 v[56:59], v1
	ds_read_b128 v[28:31], v1 offset:4096
	v_add_u32_e32 v4, v150, v157
	v_add_u32_e32 v1, v151, v157
	ds_read_b128 v[32:35], v4 offset:16384
	ds_read_b128 v[60:63], v1
	ds_read_b128 v[36:39], v1 offset:4096
	v_add_u32_e32 v8, v150, v158
	v_add_u32_e32 v1, v151, v158
	ds_read_b128 v[40:43], v8 offset:16384
	ds_read_b128 v[64:67], v1
	ds_read_b128 v[44:47], v1 offset:4096
	v_add_u32_e32 v12, v150, v159
	v_add_u32_e32 v1, v151, v159
	ds_read_b128 v[48:51], v12 offset:16384
	ds_read_b128 v[68:71], v1
	ds_read_b128 v[52:55], v1 offset:4096
	ds_read_b128 v[0:3], v0
	ds_read_b128 v[4:7], v4
	ds_read_b128 v[8:11], v8
	ds_read_b128 v[12:15], v12
	v_mov_b32_e32 v16, 0
	v_mov_b32_e32 v24, 0
	v_mov_b32_e32 v25, 0
	v_mov_b32_e32 v26, 0
	v_mov_b32_e32 v27, 0
	s_and_saveexec_b64 vcc, s[60:61]
	s_cbranch_execz .LBB0_1410
	s_waitcnt lgkmcnt(14)
	v_mfma_f32_16x16x32_bf16 v[24:27], v[20:23], v[56:59], 0
	s_waitcnt lgkmcnt(11)
	v_mfma_f32_16x16x32_bf16 v[24:27], v[32:35], v[60:63], v[24:27]
	s_waitcnt lgkmcnt(8)
	v_mfma_f32_16x16x32_bf16 v[24:27], v[40:43], v[64:67], v[24:27]
	s_waitcnt lgkmcnt(5)
	v_mfma_f32_16x16x32_bf16 v[24:27], v[48:51], v[68:71], v[24:27]

; #define LAS __attribute__((address_space(3)))
; __device__ __forceinline__ void gla_phase(LAS unsigned char* lds, const bf16_t* P, const float* hn, bf16_t* O, int G, int wg) {
;     ...
;             for (int s2 = 0; s2 < 4; ++s2) { const f32x2 p = *(const LAS f32x2*)(lds + PART + (s2 * 128 + 2 * dp) * 4); if (s2 < tq) { off0 += p.x; off1 += p.y; } bm0 += p.x; bm1 += p.y; }
; #pragma unroll
;             for (int s2 = 4; s2 < 7; ++s2) { const f32x2 p = *(const LAS f32x2*)(lds + PART + (s2 * 128 + 2 * dp) * 4); if (s2 < tq) { off0 += p.x; off1 += p.y; } }
.LBB0_1415:
	v_add_f32_e32 v77, v77, v228
	v_add_f32_e32 v32, v32, v229
	s_or_b64 exec, exec, vcc
	s_and_saveexec_b64 vcc, s[58:59]
	s_cbranch_execnz .LBB0_1407
	s_branch .LBB0_1408
